# scan phase: leave the next time-block's 16 prefetch loads in flight (vmcnt(16) instead of vmcnt(0) right after issuing them)
# speedup vs baseline: 1.0124x; 1.0124x over previous
; DI f32x4 bf4(u32x2 w) { return (f32x4){lo_f(w.x), hi_f(w.x), lo_f(w.y), hi_f(w.y)}; }
; DI f32x4 exp4(u32x2 w) { return (f32x4){__expf(lo_f(w.x)), __expf(hi_f(w.x)), __expf(lo_f(w.y)), __expf(hi_f(w.y))}; }
; DI void scan_block(const ScanLU& r, const bf16_t* gp, f32x4* sP, f32x4* sH, f32x4& cb, bf16_t* op, bool act, int sg, int l22) {
;     u32x2 gw[8];
;     if (act) {
; #pragma unroll
;         for (int s = 0; s < 8; ++s) gw[s] = *(const u32x2*)(gp + (size_t)s * (2 * LRU));
;         f32x4 P = (f32x4){1.f, 1.f, 1.f, 1.f}, H = (f32x4){0.f, 0.f, 0.f, 0.f};
; #pragma unroll
;         for (int s = 0; s < 8; ++s) { const f32x4 av = exp4(r.lw[s]); H = av * H + bf4(r.uw[s]); P = P * av; }
.LBB0_992:
	s_or_b64 exec, exec, s[52:53]
	s_waitcnt vmcnt(16)
	v_mov_b32_e32 v96, 0
	s_waitcnt vmcnt(16)
	v_lshlrev_b32_e32 v134, 16, v40
	v_and_b32_e32 v135, 0xffff0000, v40
	v_lshlrev_b32_e32 v136, 16, v41
	v_and_b32_e32 v137, 0xffff0000, v41
	v_lshlrev_b32_e32 v128, 16, v46
	v_and_b32_e32 v129, 0xffff0000, v46
	v_lshlrev_b32_e32 v130, 16, v47
	v_and_b32_e32 v131, 0xffff0000, v47
	v_lshlrev_b32_e32 v122, 16, v60
	v_and_b32_e32 v123, 0xffff0000, v60
	v_lshlrev_b32_e32 v124, 16, v61
	v_and_b32_e32 v125, 0xffff0000, v61
	v_lshlrev_b32_e32 v114, 16, v64
	v_and_b32_e32 v115, 0xffff0000, v64
	v_lshlrev_b32_e32 v116, 16, v65
	v_and_b32_e32 v117, 0xffff0000, v65
	v_lshlrev_b32_e32 v108, 16, v68
	v_and_b32_e32 v109, 0xffff0000, v68
	v_lshlrev_b32_e32 v110, 16, v69
	v_and_b32_e32 v111, 0xffff0000, v69
	v_lshlrev_b32_e32 v102, 16, v72
	v_and_b32_e32 v103, 0xffff0000, v72
	v_lshlrev_b32_e32 v104, 16, v73
	v_and_b32_e32 v105, 0xffff0000, v73
	v_lshlrev_b32_e32 v98, 16, v76
	v_and_b32_e32 v99, 0xffff0000, v76
	v_lshlrev_b32_e32 v100, 16, v77
	v_and_b32_e32 v101, 0xffff0000, v77
	v_lshlrev_b32_e32 v92, 16, v80
	v_and_b32_e32 v93, 0xffff0000, v80
	v_lshlrev_b32_e32 v94, 16, v81
	v_and_b32_e32 v95, 0xffff0000, v81
	v_mov_b32_e32 v97, 0
	v_mov_b32_e32 v138, 0
	v_mov_b32_e32 v139, 0
	v_mov_b32_e32 v132, 0
	v_mov_b32_e32 v133, 0
	v_mov_b32_e32 v126, 0
	v_mov_b32_e32 v127, 0
	v_mov_b32_e32 v120, 0
	v_mov_b32_e32 v121, 0
	v_mov_b32_e32 v118, 0
	v_mov_b32_e32 v119, 0
	v_mov_b32_e32 v112, 0
	v_mov_b32_e32 v113, 0
	v_mov_b32_e32 v106, 0
	v_mov_b32_e32 v107, 0
	s_and_saveexec_b64 s[52:53], s[8:9]
	s_cbranch_execz .LBB0_994
; DI f32x4 bf4(u32x2 w) { return (f32x4){lo_f(w.x), hi_f(w.x), lo_f(w.y), hi_f(w.y)}; }
; DI f32x4 exp4(u32x2 w) { return (f32x4){__expf(lo_f(w.x)), __expf(hi_f(w.x)), __expf(lo_f(w.y)), __expf(hi_f(w.y))}; }
; DI void scan_block(const ScanLU& r, const bf16_t* gp, f32x4* sP, f32x4* sH, f32x4& cb, bf16_t* op, bool act, int sg, int l22) {
;     ...
;     if (act) {
; #pragma unroll
;         for (int s = 0; s < 8; ++s) gw[s] = *(const u32x2*)(gp + (size_t)s * (2 * LRU));
;         f32x4 P = (f32x4){1.f, 1.f, 1.f, 1.f}, H = (f32x4){0.f, 0.f, 0.f, 0.f};
; #pragma unroll
;         for (int s = 0; s < 8; ++s) { const f32x4 av = exp4(r.lw[s]); H = av * H + bf4(r.uw[s]); P = P * av; }
;         sP[sg * 22 + l22] = P; sH[sg * 22 + l22] = H; }
	v_add_co_u32_e32 v8, vcc, 0x18dcc000, v90
	v_lshlrev_b32_e32 v3, 16, v32
	s_nop 0
	v_addc_co_u32_e32 v9, vcc, 0, v91, vcc
	v_add_co_u32_e32 v10, vcc, 0x18dce000, v90
	v_mul_f32_e32 v3, 0x3fb8aa3b, v3
	s_nop 0
	v_addc_co_u32_e32 v11, vcc, 0, v91, vcc
	v_add_co_u32_e32 v96, vcc, 0x18dd1000, v90
	s_nop 1
	v_addc_co_u32_e32 v97, vcc, 0, v91, vcc
	v_add_co_u32_e32 v106, vcc, 0x18dd4000, v90
	s_nop 1
	v_addc_co_u32_e32 v107, vcc, 0, v91, vcc
	global_load_dwordx2 v[138:139], v[8:9], off
	global_load_dwordx2 v[132:133], v[10:11], off offset:3072
	global_load_dwordx2 v[126:127], v[96:97], off offset:2048
	global_load_dwordx2 v[120:121], v[106:107], off offset:1024
	v_add_co_u32_e32 v8, vcc, 0x18dd7000, v90
	s_nop 1
	v_addc_co_u32_e32 v9, vcc, 0, v91, vcc
	v_add_co_u32_e32 v10, vcc, 0x18dd9000, v90
	s_nop 1
	v_addc_co_u32_e32 v11, vcc, 0, v91, vcc
	v_add_co_u32_e32 v96, vcc, 0x18ddc000, v90
	s_nop 1
	v_addc_co_u32_e32 v97, vcc, 0, v91, vcc
	v_add_co_u32_e32 v140, vcc, 0x18ddf000, v90
	s_nop 1
	v_addc_co_u32_e32 v141, vcc, 0, v91, vcc
	global_load_dwordx2 v[118:119], v[8:9], off
	global_load_dwordx2 v[112:113], v[10:11], off offset:3072
	global_load_dwordx2 v[106:107], v[96:97], off offset:2048
	s_nop 0
	global_load_dwordx2 v[96:97], v[140:141], off offset:1024
	v_exp_f32_e32 v8, v3
	v_and_b32_e32 v3, 0xffff0000, v32
	v_mul_f32_e32 v3, 0x3fb8aa3b, v3
	v_exp_f32_e32 v9, v3
	v_lshlrev_b32_e32 v3, 16, v33
	v_mul_f32_e32 v3, 0x3fb8aa3b, v3
	v_exp_f32_e32 v10, v3
	v_and_b32_e32 v3, 0xffff0000, v33
	v_mul_f32_e32 v3, 0x3fb8aa3b, v3
	v_exp_f32_e32 v11, v3
	v_lshlrev_b32_e32 v3, 16, v38
	v_lshlrev_b32_e32 v141, 16, v39
	v_mul_f32_e32 v3, 0x3fb8aa3b, v3
	v_mul_f32_e32 v141, 0x3fb8aa3b, v141
	v_exp_f32_e32 v140, v3
	v_and_b32_e32 v3, 0xffff0000, v38
	v_exp_f32_e32 v142, v141
	v_and_b32_e32 v141, 0xffff0000, v39
	v_mul_f32_e32 v3, 0x3fb8aa3b, v3
	v_mul_f32_e32 v141, 0x3fb8aa3b, v141
	v_exp_f32_e32 v143, v141
	v_exp_f32_e32 v141, v3
	v_lshlrev_b32_e32 v3, 16, v56
	v_mul_f32_e32 v3, 0x3fb8aa3b, v3
	v_exp_f32_e32 v154, v3
	v_and_b32_e32 v3, 0xffff0000, v56
	v_mul_f32_e32 v3, 0x3fb8aa3b, v3
	v_exp_f32_e32 v155, v3
	v_lshlrev_b32_e32 v3, 16, v57
	v_mul_f32_e32 v3, 0x3fb8aa3b, v3
	v_exp_f32_e32 v156, v3
	v_and_b32_e32 v3, 0xffff0000, v57
	v_mul_f32_e32 v3, 0x3fb8aa3b, v3
	v_pk_fma_f32 v[150:151], v[8:9], 0, v[134:135] op_sel_hi:[1,0,1]
	v_exp_f32_e32 v157, v3
	v_pk_fma_f32 v[150:151], v[140:141], v[150:151], v[128:129]
	v_pk_fma_f32 v[152:153], v[10:11], 0, v[136:137] op_sel_hi:[1,0,1]
	v_pk_mul_f32 v[8:9], v[8:9], v[140:141]
	v_pk_fma_f32 v[140:141], v[154:155], v[150:151], v[122:123]
	v_lshlrev_b32_e32 v3, 16, v62
	v_lshlrev_b32_e32 v151, 16, v63
	v_pk_fma_f32 v[152:153], v[142:143], v[152:153], v[130:131]
	v_mul_f32_e32 v3, 0x3fb8aa3b, v3
	v_mul_f32_e32 v151, 0x3fb8aa3b, v151
	v_pk_mul_f32 v[10:11], v[10:11], v[142:143]
	v_pk_fma_f32 v[142:143], v[156:157], v[152:153], v[124:125]
	v_exp_f32_e32 v150, v3
	v_and_b32_e32 v3, 0xffff0000, v62
	v_exp_f32_e32 v152, v151
	v_and_b32_e32 v151, 0xffff0000, v63
	v_mul_f32_e32 v3, 0x3fb8aa3b, v3
	v_mul_f32_e32 v151, 0x3fb8aa3b, v151
	v_exp_f32_e32 v153, v151
	v_exp_f32_e32 v151, v3
	v_lshlrev_b32_e32 v3, 16, v66
	v_mul_f32_e32 v3, 0x3fb8aa3b, v3
	v_pk_mul_f32 v[8:9], v[154:155], v[8:9]
	v_exp_f32_e32 v154, v3
	v_and_b32_e32 v3, 0xffff0000, v66
	v_mul_f32_e32 v3, 0x3fb8aa3b, v3
	v_exp_f32_e32 v155, v3
	v_lshlrev_b32_e32 v3, 16, v67
	v_mul_f32_e32 v3, 0x3fb8aa3b, v3
	v_pk_mul_f32 v[10:11], v[156:157], v[10:11]
	v_exp_f32_e32 v156, v3
	v_and_b32_e32 v3, 0xffff0000, v67
	v_mul_f32_e32 v3, 0x3fb8aa3b, v3
	v_pk_fma_f32 v[140:141], v[150:151], v[140:141], v[114:115]
	v_exp_f32_e32 v157, v3
	v_pk_mul_f32 v[8:9], v[150:151], v[8:9]
	v_lshlrev_b32_e32 v3, 16, v70
	v_lshlrev_b32_e32 v151, 16, v71
	v_mul_f32_e32 v3, 0x3fb8aa3b, v3
	v_mul_f32_e32 v151, 0x3fb8aa3b, v151
	v_pk_fma_f32 v[142:143], v[152:153], v[142:143], v[116:117]
	v_pk_mul_f32 v[10:11], v[152:153], v[10:11]
	v_exp_f32_e32 v150, v3
	v_and_b32_e32 v3, 0xffff0000, v70
	v_exp_f32_e32 v152, v151
	v_and_b32_e32 v151, 0xffff0000, v71
	v_mul_f32_e32 v3, 0x3fb8aa3b, v3
	v_mul_f32_e32 v151, 0x3fb8aa3b, v151
	v_exp_f32_e32 v153, v151
	v_exp_f32_e32 v151, v3
	v_lshlrev_b32_e32 v3, 16, v74
	v_mul_f32_e32 v3, 0x3fb8aa3b, v3
	v_pk_fma_f32 v[140:141], v[154:155], v[140:141], v[108:109]
	v_pk_mul_f32 v[8:9], v[154:155], v[8:9]
	v_exp_f32_e32 v154, v3
	v_and_b32_e32 v3, 0xffff0000, v74
	v_mul_f32_e32 v3, 0x3fb8aa3b, v3
	v_exp_f32_e32 v155, v3
	v_lshlrev_b32_e32 v3, 16, v75
	v_mul_f32_e32 v3, 0x3fb8aa3b, v3
	v_pk_fma_f32 v[142:143], v[156:157], v[142:143], v[110:111]
	v_pk_mul_f32 v[10:11], v[156:157], v[10:11]
	v_exp_f32_e32 v156, v3
	v_and_b32_e32 v3, 0xffff0000, v75
	v_mul_f32_e32 v3, 0x3fb8aa3b, v3
	v_pk_fma_f32 v[140:141], v[150:151], v[140:141], v[102:103]
	v_exp_f32_e32 v157, v3
	v_pk_mul_f32 v[8:9], v[150:151], v[8:9]
	v_lshlrev_b32_e32 v3, 16, v78
	v_lshlrev_b32_e32 v151, 16, v79
	v_mul_f32_e32 v3, 0x3fb8aa3b, v3
	v_mul_f32_e32 v151, 0x3fb8aa3b, v151
	v_pk_fma_f32 v[142:143], v[152:153], v[142:143], v[104:105]
	v_pk_mul_f32 v[10:11], v[152:153], v[10:11]
	v_exp_f32_e32 v150, v3
	v_and_b32_e32 v3, 0xffff0000, v78
	v_exp_f32_e32 v152, v151
	v_and_b32_e32 v151, 0xffff0000, v79
	v_mul_f32_e32 v3, 0x3fb8aa3b, v3
	v_mul_f32_e32 v151, 0x3fb8aa3b, v151
	v_exp_f32_e32 v153, v151
	v_exp_f32_e32 v151, v3
	v_pk_fma_f32 v[140:141], v[154:155], v[140:141], v[98:99]
	v_pk_fma_f32 v[142:143], v[156:157], v[142:143], v[100:101]
	v_pk_mul_f32 v[154:155], v[154:155], v[8:9]
	v_pk_mul_f32 v[156:157], v[156:157], v[10:11]
	v_pk_fma_f32 v[10:11], v[152:153], v[142:143], v[94:95]
	v_pk_fma_f32 v[8:9], v[150:151], v[140:141], v[92:93]
	v_pk_mul_f32 v[142:143], v[152:153], v[156:157]
	v_pk_mul_f32 v[140:141], v[150:151], v[154:155]
	ds_write_b128 v145, v[140:143]
	ds_write_b128 v145, v[8:11] offset:5632

; DI f32x4 bf4(u32x2 w) { return (f32x4){lo_f(w.x), hi_f(w.x), lo_f(w.y), hi_f(w.y)}; }
; DI f32x4 exp4(u32x2 w) { return (f32x4){__expf(lo_f(w.x)), __expf(hi_f(w.x)), __expf(lo_f(w.y)), __expf(hi_f(w.y))}; }
; DI void scan_block(const ScanLU& r, const bf16_t* gp, f32x4* sP, f32x4* sH, f32x4& cb, bf16_t* op, bool act, int sg, int l22) {
;     u32x2 gw[8];
;     if (act) {
; #pragma unroll
;         for (int s = 0; s < 8; ++s) gw[s] = *(const u32x2*)(gp + (size_t)s * (2 * LRU));
;         f32x4 P = (f32x4){1.f, 1.f, 1.f, 1.f}, H = (f32x4){0.f, 0.f, 0.f, 0.f};
; #pragma unroll
;         for (int s = 0; s < 8; ++s) { const f32x4 av = exp4(r.lw[s]); H = av * H + bf4(r.uw[s]); P = P * av; }
.LBB0_998:
	s_or_b64 exec, exec, s[54:55]
	s_waitcnt vmcnt(16)
	v_mov_b32_e32 v96, 0
	v_lshlrev_b32_e32 v134, 16, v20
	v_and_b32_e32 v135, 0xffff0000, v20
	v_lshlrev_b32_e32 v136, 16, v21
	v_and_b32_e32 v137, 0xffff0000, v21
	v_lshlrev_b32_e32 v128, 16, v24
	v_and_b32_e32 v129, 0xffff0000, v24
	v_lshlrev_b32_e32 v130, 16, v25
	v_and_b32_e32 v131, 0xffff0000, v25
	v_lshlrev_b32_e32 v122, 16, v28
	v_and_b32_e32 v123, 0xffff0000, v28
	v_lshlrev_b32_e32 v124, 16, v29
	v_and_b32_e32 v125, 0xffff0000, v29
	v_lshlrev_b32_e32 v114, 16, v34
	v_and_b32_e32 v115, 0xffff0000, v34
	v_lshlrev_b32_e32 v116, 16, v35
	v_and_b32_e32 v117, 0xffff0000, v35
	v_lshlrev_b32_e32 v108, 16, v42
	v_and_b32_e32 v109, 0xffff0000, v42
	v_lshlrev_b32_e32 v110, 16, v43
	v_and_b32_e32 v111, 0xffff0000, v43
	v_lshlrev_b32_e32 v102, 16, v48
	v_and_b32_e32 v103, 0xffff0000, v48
	v_lshlrev_b32_e32 v104, 16, v49
	v_and_b32_e32 v105, 0xffff0000, v49
	v_lshlrev_b32_e32 v98, 16, v52
	v_and_b32_e32 v99, 0xffff0000, v52
	v_lshlrev_b32_e32 v100, 16, v53
	v_and_b32_e32 v101, 0xffff0000, v53
	v_lshlrev_b32_e32 v92, 16, v58
	v_and_b32_e32 v93, 0xffff0000, v58
	v_lshlrev_b32_e32 v94, 16, v59
	v_and_b32_e32 v95, 0xffff0000, v59
	v_mov_b32_e32 v97, 0
	v_mov_b32_e32 v138, 0
	v_mov_b32_e32 v139, 0
	v_mov_b32_e32 v132, 0
	v_mov_b32_e32 v133, 0
	v_mov_b32_e32 v126, 0
	v_mov_b32_e32 v127, 0
	v_mov_b32_e32 v120, 0
	v_mov_b32_e32 v121, 0
	v_mov_b32_e32 v118, 0
	v_mov_b32_e32 v119, 0
	v_mov_b32_e32 v112, 0
	v_mov_b32_e32 v113, 0
	v_mov_b32_e32 v106, 0
	v_mov_b32_e32 v107, 0
	s_and_saveexec_b64 s[54:55], s[8:9]
	s_cbranch_execz .LBB0_1000
; DI f32x4 bf4(u32x2 w) { return (f32x4){lo_f(w.x), hi_f(w.x), lo_f(w.y), hi_f(w.y)}; }
; DI f32x4 exp4(u32x2 w) { return (f32x4){__expf(lo_f(w.x)), __expf(hi_f(w.x)), __expf(lo_f(w.y)), __expf(hi_f(w.y))}; }
; DI void scan_block(const ScanLU& r, const bf16_t* gp, f32x4* sP, f32x4* sH, f32x4& cb, bf16_t* op, bool act, int sg, int l22) {
;     ...
;     if (act) {
; #pragma unroll
;         for (int s = 0; s < 8; ++s) gw[s] = *(const u32x2*)(gp + (size_t)s * (2 * LRU));
;         f32x4 P = (f32x4){1.f, 1.f, 1.f, 1.f}, H = (f32x4){0.f, 0.f, 0.f, 0.f};
; #pragma unroll
;         for (int s = 0; s < 8; ++s) { const f32x4 av = exp4(r.lw[s]); H = av * H + bf4(r.uw[s]); P = P * av; }
;         sP[sg * 22 + l22] = P; sH[sg * 22 + l22] = H; }
	v_add_co_u32_e32 v8, vcc, 0x18f2c000, v90
	v_lshlrev_b32_e32 v3, 16, v18
	s_nop 0
	v_addc_co_u32_e32 v9, vcc, 0, v91, vcc
	v_add_co_u32_e32 v10, vcc, 0x18f2e000, v90
	v_mul_f32_e32 v3, 0x3fb8aa3b, v3
	s_nop 0
	v_addc_co_u32_e32 v11, vcc, 0, v91, vcc
	v_add_co_u32_e32 v96, vcc, 0x18f31000, v90
	s_nop 1
	v_addc_co_u32_e32 v97, vcc, 0, v91, vcc
	v_add_co_u32_e32 v106, vcc, 0x18f34000, v90
	s_nop 1
	v_addc_co_u32_e32 v107, vcc, 0, v91, vcc
	global_load_dwordx2 v[138:139], v[8:9], off
	global_load_dwordx2 v[132:133], v[10:11], off offset:3072
	global_load_dwordx2 v[126:127], v[96:97], off offset:2048
	global_load_dwordx2 v[120:121], v[106:107], off offset:1024
	v_add_co_u32_e32 v8, vcc, 0x18f37000, v90
	s_nop 1
	v_addc_co_u32_e32 v9, vcc, 0, v91, vcc
	v_add_co_u32_e32 v10, vcc, 0x18f39000, v90
	s_nop 1
	v_addc_co_u32_e32 v11, vcc, 0, v91, vcc
	v_add_co_u32_e32 v96, vcc, 0x18f3c000, v90
	s_nop 1
	v_addc_co_u32_e32 v97, vcc, 0, v91, vcc
	v_add_co_u32_e32 v90, vcc, 0x18f3f000, v90
	s_nop 1
	v_addc_co_u32_e32 v91, vcc, 0, v91, vcc
	global_load_dwordx2 v[118:119], v[8:9], off
	global_load_dwordx2 v[112:113], v[10:11], off offset:3072
	global_load_dwordx2 v[106:107], v[96:97], off offset:2048
	s_nop 0
	global_load_dwordx2 v[96:97], v[90:91], off offset:1024
	v_exp_f32_e32 v8, v3
	v_and_b32_e32 v3, 0xffff0000, v18
	v_mul_f32_e32 v3, 0x3fb8aa3b, v3
	v_exp_f32_e32 v9, v3
	v_lshlrev_b32_e32 v3, 16, v19
	v_mul_f32_e32 v3, 0x3fb8aa3b, v3
	v_exp_f32_e32 v10, v3
	v_and_b32_e32 v3, 0xffff0000, v19
	v_mul_f32_e32 v3, 0x3fb8aa3b, v3
	v_exp_f32_e32 v11, v3
	v_lshlrev_b32_e32 v3, 16, v22
	v_lshlrev_b32_e32 v91, 16, v23
	v_mul_f32_e32 v3, 0x3fb8aa3b, v3
	v_mul_f32_e32 v91, 0x3fb8aa3b, v91
	v_exp_f32_e32 v90, v3
	v_and_b32_e32 v3, 0xffff0000, v22
	v_exp_f32_e32 v140, v91
	v_and_b32_e32 v91, 0xffff0000, v23
	v_mul_f32_e32 v3, 0x3fb8aa3b, v3
	v_mul_f32_e32 v91, 0x3fb8aa3b, v91
	v_exp_f32_e32 v141, v91
	v_exp_f32_e32 v91, v3
	v_lshlrev_b32_e32 v3, 16, v26
	v_mul_f32_e32 v3, 0x3fb8aa3b, v3
	v_exp_f32_e32 v152, v3
	v_and_b32_e32 v3, 0xffff0000, v26
	v_mul_f32_e32 v3, 0x3fb8aa3b, v3
	v_exp_f32_e32 v153, v3
	v_lshlrev_b32_e32 v3, 16, v27
	v_mul_f32_e32 v3, 0x3fb8aa3b, v3
	v_exp_f32_e32 v154, v3
	v_and_b32_e32 v3, 0xffff0000, v27
	v_mul_f32_e32 v3, 0x3fb8aa3b, v3
	v_pk_fma_f32 v[142:143], v[8:9], 0, v[134:135] op_sel_hi:[1,0,1]
	v_exp_f32_e32 v155, v3
	v_pk_fma_f32 v[142:143], v[90:91], v[142:143], v[128:129]
	v_pk_fma_f32 v[150:151], v[10:11], 0, v[136:137] op_sel_hi:[1,0,1]
	v_pk_mul_f32 v[8:9], v[90:91], v[8:9]
	v_pk_fma_f32 v[90:91], v[152:153], v[142:143], v[122:123]
	v_lshlrev_b32_e32 v3, 16, v30
	v_lshlrev_b32_e32 v143, 16, v31
	v_pk_fma_f32 v[150:151], v[140:141], v[150:151], v[130:131]
	v_mul_f32_e32 v3, 0x3fb8aa3b, v3
	v_mul_f32_e32 v143, 0x3fb8aa3b, v143
	v_pk_mul_f32 v[10:11], v[140:141], v[10:11]
	v_pk_fma_f32 v[140:141], v[154:155], v[150:151], v[124:125]
	v_exp_f32_e32 v142, v3
	v_and_b32_e32 v3, 0xffff0000, v30
	v_exp_f32_e32 v150, v143
	v_and_b32_e32 v143, 0xffff0000, v31
	v_mul_f32_e32 v3, 0x3fb8aa3b, v3
	v_mul_f32_e32 v143, 0x3fb8aa3b, v143
	v_exp_f32_e32 v151, v143
	v_exp_f32_e32 v143, v3
	v_lshlrev_b32_e32 v3, 16, v36
	v_mul_f32_e32 v3, 0x3fb8aa3b, v3
	v_pk_mul_f32 v[8:9], v[152:153], v[8:9]
	v_exp_f32_e32 v152, v3
	v_and_b32_e32 v3, 0xffff0000, v36
	v_mul_f32_e32 v3, 0x3fb8aa3b, v3
	v_exp_f32_e32 v153, v3
	v_lshlrev_b32_e32 v3, 16, v37
	v_mul_f32_e32 v3, 0x3fb8aa3b, v3
	v_pk_mul_f32 v[10:11], v[154:155], v[10:11]
	v_exp_f32_e32 v154, v3
	v_and_b32_e32 v3, 0xffff0000, v37
	v_mul_f32_e32 v3, 0x3fb8aa3b, v3
	v_pk_fma_f32 v[90:91], v[142:143], v[90:91], v[114:115]
	v_exp_f32_e32 v155, v3
	v_pk_mul_f32 v[8:9], v[142:143], v[8:9]
	v_lshlrev_b32_e32 v3, 16, v44
	v_lshlrev_b32_e32 v143, 16, v45
	v_mul_f32_e32 v3, 0x3fb8aa3b, v3
	v_mul_f32_e32 v143, 0x3fb8aa3b, v143
	v_pk_fma_f32 v[140:141], v[150:151], v[140:141], v[116:117]
	v_pk_mul_f32 v[10:11], v[150:151], v[10:11]
	v_exp_f32_e32 v142, v3
	v_and_b32_e32 v3, 0xffff0000, v44
	v_exp_f32_e32 v150, v143
	v_and_b32_e32 v143, 0xffff0000, v45
	v_mul_f32_e32 v3, 0x3fb8aa3b, v3
	v_mul_f32_e32 v143, 0x3fb8aa3b, v143
	v_exp_f32_e32 v151, v143
	v_exp_f32_e32 v143, v3
	v_lshlrev_b32_e32 v3, 16, v50
	v_mul_f32_e32 v3, 0x3fb8aa3b, v3
	v_pk_fma_f32 v[90:91], v[152:153], v[90:91], v[108:109]
	v_pk_mul_f32 v[8:9], v[152:153], v[8:9]
	v_exp_f32_e32 v152, v3
	v_and_b32_e32 v3, 0xffff0000, v50
	v_mul_f32_e32 v3, 0x3fb8aa3b, v3
	v_exp_f32_e32 v153, v3
	v_lshlrev_b32_e32 v3, 16, v51
	v_mul_f32_e32 v3, 0x3fb8aa3b, v3
	v_pk_fma_f32 v[140:141], v[154:155], v[140:141], v[110:111]
	v_pk_mul_f32 v[10:11], v[154:155], v[10:11]
	v_exp_f32_e32 v154, v3
	v_and_b32_e32 v3, 0xffff0000, v51
	v_mul_f32_e32 v3, 0x3fb8aa3b, v3
	v_exp_f32_e32 v155, v3
	v_lshlrev_b32_e32 v3, 16, v54
	v_mul_f32_e32 v3, 0x3fb8aa3b, v3
	v_pk_fma_f32 v[140:141], v[150:151], v[140:141], v[104:105]
	v_pk_fma_f32 v[90:91], v[142:143], v[90:91], v[102:103]
	v_pk_mul_f32 v[10:11], v[150:151], v[10:11]
	v_pk_mul_f32 v[8:9], v[142:143], v[8:9]
	v_exp_f32_e32 v150, v3
	v_and_b32_e32 v3, 0xffff0000, v54
	v_lshlrev_b32_e32 v142, 16, v55
	v_and_b32_e32 v143, 0xffff0000, v55
	v_mul_f32_e32 v3, 0x3fb8aa3b, v3
	v_mul_f32_e32 v142, 0x3fb8aa3b, v142
	v_mul_f32_e32 v143, 0x3fb8aa3b, v143
	v_exp_f32_e32 v142, v142
	v_exp_f32_e32 v143, v143
	v_exp_f32_e32 v151, v3
	v_pk_fma_f32 v[90:91], v[152:153], v[90:91], v[98:99]
	v_pk_fma_f32 v[140:141], v[154:155], v[140:141], v[100:101]
	v_pk_mul_f32 v[152:153], v[152:153], v[8:9]
	v_pk_mul_f32 v[154:155], v[154:155], v[10:11]
	v_pk_fma_f32 v[10:11], v[142:143], v[140:141], v[94:95]
	v_pk_mul_f32 v[142:143], v[142:143], v[154:155]
	v_pk_mul_f32 v[140:141], v[150:151], v[152:153]
	v_pk_fma_f32 v[8:9], v[150:151], v[90:91], v[92:93]
	ds_write_b128 v145, v[140:143] offset:11264
	ds_write_b128 v145, v[8:11] offset:16896
